# in_proj per-head scalar columns (f,a,b): replaced 8x-redundant split-K side GEMM (2 x 256x256 units per WG) by a direct 32-row x 48-col bf16 MFMA kernel, K split over 8 waves, f32 LDS reduce + f32 epi
# speedup vs baseline: 1.0169x; 1.0005x over previous
.LBB0_443:
	s_barrier
	v_readfirstlane_b32 s4, v0
	v_and_b32_e32 v1, 63, v0
	s_lshr_b32 s4, s4, 6
	v_and_b32_e32 v2, 15, v1
	v_lshrrev_b32_e32 v3, 4, v1
	v_lshlrev_b32_e32 v4, 13, v2
	v_lshl_or_b32 v4, v3, 4, v4
	s_lshl_b32 s5, s4, 10
	s_lshl_b32 s16, s95, 18
	s_add_u32 s6, s82, 0x1c800000
	s_addc_u32 s7, s83, 0
	s_add_u32 s6, s6, s16
	s_addc_u32 s7, s7, 0
	s_add_u32 s6, s6, s5
	s_addc_u32 s7, s7, 0
	s_add_u32 s10, s6, 0x20000
	s_addc_u32 s11, s7, 0
	s_add_u32 s8, s82, 0x9000000
	s_addc_u32 s9, s83, 0
	s_add_u32 s8, s8, s5
	s_addc_u32 s9, s9, 0
	s_add_u32 s12, s8, 0x20000
	s_addc_u32 s13, s9, 0
	s_add_u32 s14, s8, 0x40000
	s_addc_u32 s15, s9, 0
	global_load_dwordx4 v[32:35], v4, s[6:7]
	global_load_dwordx4 v[36:39], v4, s[10:11]
	global_load_dwordx4 v[40:43], v4, s[8:9]
	global_load_dwordx4 v[44:47], v4, s[12:13]
	global_load_dwordx4 v[48:51], v4, s[14:15]
	global_load_dwordx4 v[52:55], v4, s[6:7] offset:64
	global_load_dwordx4 v[56:59], v4, s[10:11] offset:64
	global_load_dwordx4 v[60:63], v4, s[8:9] offset:64
	global_load_dwordx4 v[64:67], v4, s[12:13] offset:64
	global_load_dwordx4 v[68:71], v4, s[14:15] offset:64
	global_load_dwordx4 v[72:75], v4, s[6:7] offset:128
	global_load_dwordx4 v[76:79], v4, s[10:11] offset:128
	global_load_dwordx4 v[80:83], v4, s[8:9] offset:128
	global_load_dwordx4 v[84:87], v4, s[12:13] offset:128
	global_load_dwordx4 v[88:91], v4, s[14:15] offset:128
	global_load_dwordx4 v[92:95], v4, s[6:7] offset:192
	global_load_dwordx4 v[96:99], v4, s[10:11] offset:192
	global_load_dwordx4 v[100:103], v4, s[8:9] offset:192
	global_load_dwordx4 v[104:107], v4, s[12:13] offset:192
	global_load_dwordx4 v[108:111], v4, s[14:15] offset:192
	global_load_dwordx4 v[112:115], v4, s[6:7] offset:256
	global_load_dwordx4 v[116:119], v4, s[10:11] offset:256
	global_load_dwordx4 v[120:123], v4, s[8:9] offset:256
	global_load_dwordx4 v[124:127], v4, s[12:13] offset:256
	global_load_dwordx4 v[128:131], v4, s[14:15] offset:256
	global_load_dwordx4 v[132:135], v4, s[6:7] offset:320
	global_load_dwordx4 v[136:139], v4, s[10:11] offset:320
	global_load_dwordx4 v[140:143], v4, s[8:9] offset:320
	global_load_dwordx4 v[144:147], v4, s[12:13] offset:320
	global_load_dwordx4 v[148:151], v4, s[14:15] offset:320
	global_load_dwordx4 v[152:155], v4, s[6:7] offset:384
	global_load_dwordx4 v[156:159], v4, s[10:11] offset:384
	global_load_dwordx4 v[160:163], v4, s[8:9] offset:384
	global_load_dwordx4 v[164:167], v4, s[12:13] offset:384
	global_load_dwordx4 v[168:171], v4, s[14:15] offset:384
	global_load_dwordx4 v[172:175], v4, s[6:7] offset:448
	global_load_dwordx4 v[176:179], v4, s[10:11] offset:448
	global_load_dwordx4 v[180:183], v4, s[8:9] offset:448
	global_load_dwordx4 v[184:187], v4, s[12:13] offset:448
	global_load_dwordx4 v[188:191], v4, s[14:15] offset:448
	v_mov_b32_e32 v192, 0
	v_mov_b32_e32 v193, 0
	v_mov_b32_e32 v194, 0
	v_mov_b32_e32 v195, 0
	v_mov_b32_e32 v196, 0
	v_mov_b32_e32 v197, 0
	v_mov_b32_e32 v198, 0
	v_mov_b32_e32 v199, 0
	v_mov_b32_e32 v200, 0
	v_mov_b32_e32 v201, 0
	v_mov_b32_e32 v202, 0
	v_mov_b32_e32 v203, 0
	v_mov_b32_e32 v204, 0
	v_mov_b32_e32 v205, 0
	v_mov_b32_e32 v206, 0
	v_mov_b32_e32 v207, 0
	v_mov_b32_e32 v208, 0
	v_mov_b32_e32 v209, 0
	v_mov_b32_e32 v210, 0
	v_mov_b32_e32 v211, 0
	v_mov_b32_e32 v212, 0
	v_mov_b32_e32 v213, 0
	v_mov_b32_e32 v214, 0
	v_mov_b32_e32 v215, 0
	s_waitcnt vmcnt(20)
	v_mfma_f32_16x16x32_bf16 v[192:195], v[32:35], v[40:43], v[192:195]
	v_mfma_f32_16x16x32_bf16 v[196:199], v[32:35], v[44:47], v[196:199]
	v_mfma_f32_16x16x32_bf16 v[200:203], v[32:35], v[48:51], v[200:203]
	v_mfma_f32_16x16x32_bf16 v[204:207], v[36:39], v[40:43], v[204:207]
	v_mfma_f32_16x16x32_bf16 v[208:211], v[36:39], v[44:47], v[208:211]
	v_mfma_f32_16x16x32_bf16 v[212:215], v[36:39], v[48:51], v[212:215]
	v_mfma_f32_16x16x32_bf16 v[192:195], v[52:55], v[60:63], v[192:195]
	v_mfma_f32_16x16x32_bf16 v[196:199], v[52:55], v[64:67], v[196:199]
	v_mfma_f32_16x16x32_bf16 v[200:203], v[52:55], v[68:71], v[200:203]
	v_mfma_f32_16x16x32_bf16 v[204:207], v[56:59], v[60:63], v[204:207]
	v_mfma_f32_16x16x32_bf16 v[208:211], v[56:59], v[64:67], v[208:211]
	v_mfma_f32_16x16x32_bf16 v[212:215], v[56:59], v[68:71], v[212:215]
	v_mfma_f32_16x16x32_bf16 v[192:195], v[72:75], v[80:83], v[192:195]
	v_mfma_f32_16x16x32_bf16 v[196:199], v[72:75], v[84:87], v[196:199]
	v_mfma_f32_16x16x32_bf16 v[200:203], v[72:75], v[88:91], v[200:203]
	v_mfma_f32_16x16x32_bf16 v[204:207], v[76:79], v[80:83], v[204:207]
	v_mfma_f32_16x16x32_bf16 v[208:211], v[76:79], v[84:87], v[208:211]
	v_mfma_f32_16x16x32_bf16 v[212:215], v[76:79], v[88:91], v[212:215]
	v_mfma_f32_16x16x32_bf16 v[192:195], v[92:95], v[100:103], v[192:195]
	v_mfma_f32_16x16x32_bf16 v[196:199], v[92:95], v[104:107], v[196:199]
	v_mfma_f32_16x16x32_bf16 v[200:203], v[92:95], v[108:111], v[200:203]
	v_mfma_f32_16x16x32_bf16 v[204:207], v[96:99], v[100:103], v[204:207]
	v_mfma_f32_16x16x32_bf16 v[208:211], v[96:99], v[104:107], v[208:211]
	v_mfma_f32_16x16x32_bf16 v[212:215], v[96:99], v[108:111], v[212:215]
	global_load_dwordx4 v[32:35], v4, s[6:7] offset:512
	global_load_dwordx4 v[36:39], v4, s[10:11] offset:512
	global_load_dwordx4 v[40:43], v4, s[8:9] offset:512
	global_load_dwordx4 v[44:47], v4, s[12:13] offset:512
	global_load_dwordx4 v[48:51], v4, s[14:15] offset:512
	global_load_dwordx4 v[52:55], v4, s[6:7] offset:576
	global_load_dwordx4 v[56:59], v4, s[10:11] offset:576
	global_load_dwordx4 v[60:63], v4, s[8:9] offset:576
	global_load_dwordx4 v[64:67], v4, s[12:13] offset:576
	global_load_dwordx4 v[68:71], v4, s[14:15] offset:576
	global_load_dwordx4 v[72:75], v4, s[6:7] offset:640
	global_load_dwordx4 v[76:79], v4, s[10:11] offset:640
	global_load_dwordx4 v[80:83], v4, s[8:9] offset:640
	global_load_dwordx4 v[84:87], v4, s[12:13] offset:640
	global_load_dwordx4 v[88:91], v4, s[14:15] offset:640
	global_load_dwordx4 v[92:95], v4, s[6:7] offset:704
	global_load_dwordx4 v[96:99], v4, s[10:11] offset:704
	global_load_dwordx4 v[100:103], v4, s[8:9] offset:704
	global_load_dwordx4 v[104:107], v4, s[12:13] offset:704
	global_load_dwordx4 v[108:111], v4, s[14:15] offset:704
	s_waitcnt vmcnt(20)
	v_mfma_f32_16x16x32_bf16 v[192:195], v[112:115], v[120:123], v[192:195]
	v_mfma_f32_16x16x32_bf16 v[196:199], v[112:115], v[124:127], v[196:199]
	v_mfma_f32_16x16x32_bf16 v[200:203], v[112:115], v[128:131], v[200:203]
	v_mfma_f32_16x16x32_bf16 v[204:207], v[116:119], v[120:123], v[204:207]
	v_mfma_f32_16x16x32_bf16 v[208:211], v[116:119], v[124:127], v[208:211]
	v_mfma_f32_16x16x32_bf16 v[212:215], v[116:119], v[128:131], v[212:215]
	v_mfma_f32_16x16x32_bf16 v[192:195], v[132:135], v[140:143], v[192:195]
	v_mfma_f32_16x16x32_bf16 v[196:199], v[132:135], v[144:147], v[196:199]
	v_mfma_f32_16x16x32_bf16 v[200:203], v[132:135], v[148:151], v[200:203]
	v_mfma_f32_16x16x32_bf16 v[204:207], v[136:139], v[140:143], v[204:207]
	v_mfma_f32_16x16x32_bf16 v[208:211], v[136:139], v[144:147], v[208:211]
	v_mfma_f32_16x16x32_bf16 v[212:215], v[136:139], v[148:151], v[212:215]
	v_mfma_f32_16x16x32_bf16 v[192:195], v[152:155], v[160:163], v[192:195]
	v_mfma_f32_16x16x32_bf16 v[196:199], v[152:155], v[164:167], v[196:199]
	v_mfma_f32_16x16x32_bf16 v[200:203], v[152:155], v[168:171], v[200:203]
	v_mfma_f32_16x16x32_bf16 v[204:207], v[156:159], v[160:163], v[204:207]
	v_mfma_f32_16x16x32_bf16 v[208:211], v[156:159], v[164:167], v[208:211]
	v_mfma_f32_16x16x32_bf16 v[212:215], v[156:159], v[168:171], v[212:215]
	v_mfma_f32_16x16x32_bf16 v[192:195], v[172:175], v[180:183], v[192:195]
	v_mfma_f32_16x16x32_bf16 v[196:199], v[172:175], v[184:187], v[196:199]
	v_mfma_f32_16x16x32_bf16 v[200:203], v[172:175], v[188:191], v[200:203]
	v_mfma_f32_16x16x32_bf16 v[204:207], v[176:179], v[180:183], v[204:207]
	v_mfma_f32_16x16x32_bf16 v[208:211], v[176:179], v[184:187], v[208:211]
	v_mfma_f32_16x16x32_bf16 v[212:215], v[176:179], v[188:191], v[212:215]
	global_load_dwordx4 v[112:115], v4, s[6:7] offset:768
	global_load_dwordx4 v[116:119], v4, s[10:11] offset:768
	global_load_dwordx4 v[120:123], v4, s[8:9] offset:768
	global_load_dwordx4 v[124:127], v4, s[12:13] offset:768
	global_load_dwordx4 v[128:131], v4, s[14:15] offset:768
	global_load_dwordx4 v[132:135], v4, s[6:7] offset:832
	global_load_dwordx4 v[136:139], v4, s[10:11] offset:832
	global_load_dwordx4 v[140:143], v4, s[8:9] offset:832
	global_load_dwordx4 v[144:147], v4, s[12:13] offset:832
	global_load_dwordx4 v[148:151], v4, s[14:15] offset:832
	global_load_dwordx4 v[152:155], v4, s[6:7] offset:896
	global_load_dwordx4 v[156:159], v4, s[10:11] offset:896
	global_load_dwordx4 v[160:163], v4, s[8:9] offset:896
	global_load_dwordx4 v[164:167], v4, s[12:13] offset:896
	global_load_dwordx4 v[168:171], v4, s[14:15] offset:896
	global_load_dwordx4 v[172:175], v4, s[6:7] offset:960
	global_load_dwordx4 v[176:179], v4, s[10:11] offset:960
	global_load_dwordx4 v[180:183], v4, s[8:9] offset:960
	global_load_dwordx4 v[184:187], v4, s[12:13] offset:960
	global_load_dwordx4 v[188:191], v4, s[14:15] offset:960
	s_waitcnt vmcnt(20)
	v_mfma_f32_16x16x32_bf16 v[192:195], v[32:35], v[40:43], v[192:195]
	v_mfma_f32_16x16x32_bf16 v[196:199], v[32:35], v[44:47], v[196:199]
	v_mfma_f32_16x16x32_bf16 v[200:203], v[32:35], v[48:51], v[200:203]
	v_mfma_f32_16x16x32_bf16 v[204:207], v[36:39], v[40:43], v[204:207]
	v_mfma_f32_16x16x32_bf16 v[208:211], v[36:39], v[44:47], v[208:211]
	v_mfma_f32_16x16x32_bf16 v[212:215], v[36:39], v[48:51], v[212:215]
	v_mfma_f32_16x16x32_bf16 v[192:195], v[52:55], v[60:63], v[192:195]
	v_mfma_f32_16x16x32_bf16 v[196:199], v[52:55], v[64:67], v[196:199]
	v_mfma_f32_16x16x32_bf16 v[200:203], v[52:55], v[68:71], v[200:203]
	v_mfma_f32_16x16x32_bf16 v[204:207], v[56:59], v[60:63], v[204:207]
	v_mfma_f32_16x16x32_bf16 v[208:211], v[56:59], v[64:67], v[208:211]
	v_mfma_f32_16x16x32_bf16 v[212:215], v[56:59], v[68:71], v[212:215]
	v_mfma_f32_16x16x32_bf16 v[192:195], v[72:75], v[80:83], v[192:195]
	v_mfma_f32_16x16x32_bf16 v[196:199], v[72:75], v[84:87], v[196:199]
	v_mfma_f32_16x16x32_bf16 v[200:203], v[72:75], v[88:91], v[200:203]
	v_mfma_f32_16x16x32_bf16 v[204:207], v[76:79], v[80:83], v[204:207]
	v_mfma_f32_16x16x32_bf16 v[208:211], v[76:79], v[84:87], v[208:211]
	v_mfma_f32_16x16x32_bf16 v[212:215], v[76:79], v[88:91], v[212:215]
	v_mfma_f32_16x16x32_bf16 v[192:195], v[92:95], v[100:103], v[192:195]
	v_mfma_f32_16x16x32_bf16 v[196:199], v[92:95], v[104:107], v[196:199]
	v_mfma_f32_16x16x32_bf16 v[200:203], v[92:95], v[108:111], v[200:203]
	v_mfma_f32_16x16x32_bf16 v[204:207], v[96:99], v[100:103], v[204:207]
	v_mfma_f32_16x16x32_bf16 v[208:211], v[96:99], v[104:107], v[208:211]
	v_mfma_f32_16x16x32_bf16 v[212:215], v[96:99], v[108:111], v[212:215]
	s_waitcnt vmcnt(0)
	v_mfma_f32_16x16x32_bf16 v[192:195], v[112:115], v[120:123], v[192:195]
	v_mfma_f32_16x16x32_bf16 v[196:199], v[112:115], v[124:127], v[196:199]
	v_mfma_f32_16x16x32_bf16 v[200:203], v[112:115], v[128:131], v[200:203]
	v_mfma_f32_16x16x32_bf16 v[204:207], v[116:119], v[120:123], v[204:207]
	v_mfma_f32_16x16x32_bf16 v[208:211], v[116:119], v[124:127], v[208:211]
	v_mfma_f32_16x16x32_bf16 v[212:215], v[116:119], v[128:131], v[212:215]
	v_mfma_f32_16x16x32_bf16 v[192:195], v[132:135], v[140:143], v[192:195]
	v_mfma_f32_16x16x32_bf16 v[196:199], v[132:135], v[144:147], v[196:199]
	v_mfma_f32_16x16x32_bf16 v[200:203], v[132:135], v[148:151], v[200:203]
	v_mfma_f32_16x16x32_bf16 v[204:207], v[136:139], v[140:143], v[204:207]
	v_mfma_f32_16x16x32_bf16 v[208:211], v[136:139], v[144:147], v[208:211]
	v_mfma_f32_16x16x32_bf16 v[212:215], v[136:139], v[148:151], v[212:215]
	v_mfma_f32_16x16x32_bf16 v[192:195], v[152:155], v[160:163], v[192:195]
	v_mfma_f32_16x16x32_bf16 v[196:199], v[152:155], v[164:167], v[196:199]
	v_mfma_f32_16x16x32_bf16 v[200:203], v[152:155], v[168:171], v[200:203]
	v_mfma_f32_16x16x32_bf16 v[204:207], v[156:159], v[160:163], v[204:207]
	v_mfma_f32_16x16x32_bf16 v[208:211], v[156:159], v[164:167], v[208:211]
	v_mfma_f32_16x16x32_bf16 v[212:215], v[156:159], v[168:171], v[212:215]
	v_mfma_f32_16x16x32_bf16 v[192:195], v[172:175], v[180:183], v[192:195]
	v_mfma_f32_16x16x32_bf16 v[196:199], v[172:175], v[184:187], v[196:199]
	v_mfma_f32_16x16x32_bf16 v[200:203], v[172:175], v[188:191], v[200:203]
	v_mfma_f32_16x16x32_bf16 v[204:207], v[176:179], v[180:183], v[204:207]
	v_mfma_f32_16x16x32_bf16 v[208:211], v[176:179], v[184:187], v[208:211]
	v_mfma_f32_16x16x32_bf16 v[212:215], v[176:179], v[188:191], v[212:215]
	s_mul_i32 s17, s4, 0x1800
	v_lshl_add_u32 v216, v1, 4, s17
	s_nop 7
	s_nop 3
	ds_write_b128 v216, v[192:195]
	ds_write_b128 v216, v[196:199] offset:1024
	ds_write_b128 v216, v[200:203] offset:2048
	ds_write_b128 v216, v[204:207] offset:3072
	ds_write_b128 v216, v[208:211] offset:4096
	ds_write_b128 v216, v[212:215] offset:5120
	s_waitcnt lgkmcnt(0)
	s_barrier
;     __device__ __forceinline__ void operator()(const f32x4 (&acc)[2][2][4][2], const Unit& u, int wr, int wc, int fr, int fq) const {
;     ...
;         const int row = 32 * u.pm + 16 * (ks >> 2) + 8 * wr + 2 * (ks & 3) + (fr >> 3), b = row / seq, t = row % seq;
; #pragma unroll
;         for (int j = 0; j < 4; ++j) { const int col = 32 * u.pn + 16 * (j >> 1) + 4 * wc + 2 * (j & 1) + (fq >> 1);
;             if (col < 48) { const int h = col & 15; const size_t o = (size_t)(b * nh + h) * seq + t; const float v = mine[j];
;                 if (col < 16) { const float z = v + f_bias[h]; FLS[o] = (z < 0.f ? z : 0.f) - log1pf(expf(-fabsf(z))); }
;                 else if (col < 32) { const float xs = v + dt_bias[h]; const float sp_ = xs > 20.f ? xs : log1pf(expf(xs)); GG[o] = -expf(a_log[h]) * sp_; }
;                 else GB[o] = 1.0f / (1.0f + expf(-v)); } }
	v_lshrrev_b32_e32 v5, 8, v0
	v_and_b32_e32 v6, 0xff, v0
	v_mul_u32_u24_e32 v7, 0xc00, v5
	v_lshl_add_u32 v217, v6, 2, v7
	v_bfe_u32 v8, v0, 2, 4
	v_lshlrev_b32_e32 v9, 2, v8
	v_readlane_b32 s20, v252, 18
	v_readlane_b32 s21, v252, 19
	v_readlane_b32 s22, v252, 22
	v_readlane_b32 s23, v252, 23
	v_readlane_b32 s24, v252, 24
	v_readlane_b32 s25, v252, 25
	v_bfe_u32 v10, v0, 6, 2
	v_and_b32_e32 v11, 3, v0
	v_lshl_add_u32 v10, v10, 2, v11
	v_lshl_add_u32 v10, v5, 4, v10
	s_lshl_b32 s26, s95, 5
	s_and_b32 s27, s26, 0xfff
	s_lshr_b32 s26, s26, 12
	v_add_u32_e32 v10, s27, v10
	v_lshl_add_u32 v10, v8, 12, v10
	s_lshl_b32 s26, s26, 16
	v_add_u32_e32 v10, s26, v10
	v_lshlrev_b32_e32 v10, 2, v10
	global_load_dword v12, v9, s[20:21]
	global_load_dword v13, v9, s[22:23]
	global_load_dword v14, v9, s[24:25]
	ds_read_b32 v20, v217
	ds_read_b32 v21, v217 offset:6144
	ds_read_b32 v22, v217 offset:12288
	ds_read_b32 v23, v217 offset:18432
	ds_read_b32 v24, v217 offset:24576
	ds_read_b32 v25, v217 offset:30720
	ds_read_b32 v26, v217 offset:36864
	ds_read_b32 v27, v217 offset:43008
	ds_read_b32 v28, v217 offset:1024
	ds_read_b32 v29, v217 offset:7168
	ds_read_b32 v30, v217 offset:13312
	ds_read_b32 v31, v217 offset:19456
	ds_read_b32 v32, v217 offset:25600
	ds_read_b32 v33, v217 offset:31744
	ds_read_b32 v34, v217 offset:37888
	ds_read_b32 v35, v217 offset:44032
	ds_read_b32 v36, v217 offset:2048
	ds_read_b32 v37, v217 offset:8192
	ds_read_b32 v38, v217 offset:14336
	ds_read_b32 v39, v217 offset:20480
	ds_read_b32 v40, v217 offset:26624
	ds_read_b32 v41, v217 offset:32768
	ds_read_b32 v42, v217 offset:38912
	ds_read_b32 v43, v217 offset:45056
	s_waitcnt lgkmcnt(0)
	v_add_f32_e32 v20, v20, v21
	v_add_f32_e32 v20, v20, v22
	v_add_f32_e32 v20, v20, v23
	v_add_f32_e32 v20, v20, v24
	v_add_f32_e32 v20, v20, v25
	v_add_f32_e32 v20, v20, v26
	v_add_f32_e32 v20, v20, v27
	v_add_f32_e32 v28, v28, v29
	v_add_f32_e32 v28, v28, v30
	v_add_f32_e32 v28, v28, v31
	v_add_f32_e32 v28, v28, v32
	v_add_f32_e32 v28, v28, v33
	v_add_f32_e32 v28, v28, v34
	v_add_f32_e32 v28, v28, v35
	v_add_f32_e32 v36, v36, v37
	v_add_f32_e32 v36, v36, v38
	v_add_f32_e32 v36, v36, v39
	v_add_f32_e32 v36, v36, v40
	v_add_f32_e32 v36, v36, v41
	v_add_f32_e32 v36, v36, v42
	v_add_f32_e32 v36, v36, v43
	s_add_u32 s28, s82, 0x200000
	s_addc_u32 s29, s83, 0
	s_add_u32 s30, s82, 0x300000
	s_addc_u32 s31, s83, 0
	s_add_u32 s34, s82, 0x400000
	s_addc_u32 s35, s83, 0
	v_mov_b32_e32 v50, 0x3fb8aa3b
	v_mov_b32_e32 v51, 0x32a57060
	v_mov_b32_e32 v52, 0x3f317218
	s_waitcnt vmcnt(0)
	v_add_f32_e32 v20, v20, v12
	v_sub_f32_e64 v53, 0, |v20|
	v_mul_f32_e32 v55, v53, v50
	v_fma_f32 v56, v53, v50, -v55
	v_fmac_f32_e32 v56, v53, v51
	v_exp_f32_e32 v55, v55
	v_mul_f32_e32 v56, v56, v52
	v_fma_f32 v54, v55, v56, v55
	v_add_f32_e32 v58, 1.0, v54
	v_add_f32_e32 v59, -1.0, v58
	v_log_f32_e32 v60, v58
	v_rcp_f32_e32 v58, v59
	v_mul_f32_e32 v60, v60, v52
	v_mul_f32_e32 v58, v58, v54
	v_cmp_eq_f32_e32 vcc, 0, v59
	v_mul_f32_e32 v60, v60, v58
	s_nop 1
	v_cndmask_b32_e32 v57, v60, v54, vcc
	v_min_f32_e32 v20, 0, v20
	v_sub_f32_e32 v20, v20, v57
	global_store_dword v10, v20, s[28:29]
	v_add_f32_e32 v28, v28, v14
	v_min_f32_e32 v53, 0x41a00000, v28
	v_mul_f32_e32 v55, v53, v50
	v_fma_f32 v56, v53, v50, -v55
	v_fmac_f32_e32 v56, v53, v51
	v_exp_f32_e32 v55, v55
	v_mul_f32_e32 v56, v56, v52
	v_fma_f32 v54, v55, v56, v55
	v_add_f32_e32 v58, 1.0, v54
	v_add_f32_e32 v59, -1.0, v58
	v_log_f32_e32 v60, v58
	v_rcp_f32_e32 v58, v59
	v_mul_f32_e32 v60, v60, v52
	v_mul_f32_e32 v58, v58, v54
	v_cmp_eq_f32_e32 vcc, 0, v59
	v_mul_f32_e32 v60, v60, v58
	s_nop 1
	v_cndmask_b32_e32 v57, v60, v54, vcc
	v_cmp_lt_f32_e32 vcc, 0x41a00000, v28
	s_nop 1
	v_cndmask_b32_e32 v57, v57, v28, vcc
	v_mul_f32_e32 v55, v13, v50
	v_fma_f32 v56, v13, v50, -v55
	v_fmac_f32_e32 v56, v13, v51
	v_exp_f32_e32 v55, v55
	v_mul_f32_e32 v56, v56, v52
	v_fma_f32 v54, v55, v56, v55
	v_mul_f32_e64 v28, -v54, v57
	global_store_dword v10, v28, s[30:31]
	v_max_f32_e32 v36, 0xc2a00000, v36
	v_sub_f32_e32 v53, 0, v36
	v_mul_f32_e32 v55, v53, v50
	v_fma_f32 v56, v53, v50, -v55
	v_fmac_f32_e32 v56, v53, v51
	v_exp_f32_e32 v55, v55
	v_mul_f32_e32 v56, v56, v52
	v_fma_f32 v54, v55, v56, v55
	v_add_f32_e32 v54, 1.0, v54
	v_rcp_f32_e32 v55, v54
	s_nop 0
	v_fma_f32 v56, -v54, v55, 1.0
	v_fma_f32 v55, v55, v56, v55
	global_store_dword v10, v55, s[34:35]
	s_cmp_lt_i32 s87, 6
	s_cbranch_scc1 .LBB0_884
